# quarter-tile GEMM tails (P10, P14) software-pipelined: LDS fragment reads of K-tile t+1 overlap MFMAs of K-tile t, LDS-DMA issue interleaved between MFMAs
# speedup vs baseline: 1.0099x; 1.0099x over previous
.LBB0_1711:
	s_and_b32 s4, s2, 7
	s_mul_i32 s4, s4, 12
	s_ashr_i32 s10, s2, 3
	s_add_i32 s4, s4, s10
	s_ashr_i32 s4, s4, 2
	s_addk_i32 s4, 0xc00
	s_ashr_i32 s5, s4, 31
	s_lshr_b32 s5, s5, 29
	s_add_i32 s5, s4, s5
	s_ashr_i32 s11, s5, 3
	s_and_b32 s5, s5, -8
	s_sub_i32 s4, s4, s5
	s_cmp_lt_i32 s4, 0
	s_movk_i32 s5, 0x184
	s_cselect_b32 s5, s5, 0x183
	s_mul_i32 s4, s4, s5
	s_add_i32 s36, s4, s11
	s_mul_hi_i32 s4, s36, 0x2fa0be83
	s_lshr_b32 s5, s4, 31
	s_ashr_i32 s4, s4, 7
	s_add_i32 s37, s4, s5
	s_lshl_b32 s11, s37, 3
	s_sub_i32 s4, 36, s11
	s_min_u32 s14, s4, 8
	s_mul_i32 s53, s37, 0x2b0
	s_sub_i32 s15, s36, s53
	v_cvt_f32_ubyte0_e32 v3, s14
	v_cvt_f32_i32_e32 v2, s15
	v_rcp_iflag_f32_e32 v4, v3
	s_ashr_i32 s4, s15, 30
	s_or_b32 s16, s4, 1
	v_bfe_u32 v12, v0, 2, 4
	v_mul_f32_e32 v4, v2, v4
	v_trunc_f32_e32 v4, v4
	v_fma_f32 v2, -v4, v3, v2
	v_cvt_i32_f32_e32 v4, v4
	v_cmp_ge_f32_e64 s[4:5], |v2|, v3
	s_and_b64 s[4:5], s[4:5], exec
	s_cselect_b32 s4, s16, 0
	v_readfirstlane_b32 s5, v4
	s_add_i32 s4, s5, s4
	s_mul_i32 s54, s4, s14
	v_lshlrev_b32_e32 v2, 4, v0
	v_and_b32_e32 v3, 32, v0
	s_sext_i32_i16 s5, s4
	s_sub_i32 s4, s15, s54
	v_bitop3_b32 v13, v2, v3, 48 bitop3:0x6c
	v_lshrrev_b32_e32 v3, 5, v0
	v_bfe_u32 v4, v0, 2, 2
	s_sext_i32_i16 s4, s4
	v_and_or_b32 v16, v3, 4, v4
	v_lshrrev_b32_e32 v4, 3, v0
	s_add_i32 s11, s11, s4
	s_bfe_u32 s55, s10, 0x10001
	s_lshl_b32 s5, s5, 1
	s_and_b32 s10, s10, 1
	v_and_b32_e32 v14, 64, v0
	v_or_b32_e32 v3, v16, v131
	v_and_b32_e32 v17, 32, v4
	s_waitcnt lgkmcnt(0)
	v_or_b32_e32 v18, 0x2000, v2
	s_lshl_b32 s4, s11, 1
	s_or_b32 s10, s5, s10
	v_readfirstlane_b32 s16, v0
	v_or_b32_e32 v15, v13, v14
	v_and_or_b32 v5, v4, 48, v12
	v_or_b32_e32 v4, v3, v17
	v_lshrrev_b32_e32 v2, 7, v18
	s_movk_i32 s5, 0x70
	s_or_b32 s4, s4, s55
	v_lshl_or_b32 v36, v4, 13, v15
	v_and_or_b32 v4, v2, s5, v12
	s_lshr_b32 s5, s16, 2
	s_and_b32 s20, s5, 0x3fffffc0
	s_ashr_i32 s5, s4, 31
	s_lshr_b32 s17, s16, 1
	s_lshl_b64 s[14:15], s[4:5], 20
	s_lshl_b32 s5, s16, 4
	s_ashr_i32 s11, s10, 31
	s_and_b32 s43, s5, 0xfffffc00
	s_and_b32 s5, s17, 0x60
	s_lshl_b64 s[18:19], s[10:11], 20
	s_lshl_b32 s58, s20, 7
	s_lshl_b32 s59, s5, 7
	s_add_u32 s14, s3, s14
	s_addc_u32 s15, s33, s15
	s_add_u32 s16, s27, s18
	s_addc_u32 s17, s41, s19
	s_add_i32 s11, s43, 0
	s_add_i32 s50, 0, 0x10000
	v_lshl_or_b32 v34, v5, 13, v15
	v_and_b32_e32 v19, 0x60, v2
	s_add_i32 s24, s50, s43
	s_mov_b32 m0, s11
	v_or_b32_e32 v2, v3, v19
	global_load_lds_dwordx4 v34, s[14:15]
	s_mov_b32 m0, s24
	s_add_i32 s21, s11, 0x2000
	v_lshl_or_b32 v38, v4, 13, v15
	v_lshl_or_b32 v40, v2, 13, v15
	v_lshlrev_b32_e32 v2, 2, v163
	v_mov_b32_e32 v35, 0
	global_load_lds_dwordx4 v36, s[16:17]
	s_mov_b32 m0, s21
	v_and_b32_e32 v21, 32, v2
	v_lshl_add_u64 v[2:3], s[14:15], 0, v[34:35]
	v_mov_b32_e32 v37, v35
	global_load_lds_dwordx4 v38, s[14:15]
	s_add_i32 m0, s24, 0x2000
	s_add_i32 s24, s11, 0x4000
	s_add_i32 s51, 0, 0x14000
	s_mov_b64 s[38:39], 0x80
	v_lshl_add_u64 v[4:5], s[16:17], 0, v[36:37]
	v_mov_b32_e32 v39, v35
	global_load_lds_dwordx4 v40, s[16:17]
	s_add_i32 s27, s51, s43
	v_lshl_add_u64 v[10:11], v[2:3], 0, s[38:39]
	s_mov_b32 m0, s24
	v_lshl_add_u64 v[6:7], s[14:15], 0, v[38:39]
	v_mov_b32_e32 v41, v35
	global_load_lds_dwordx4 v[10:11], off
	v_lshl_add_u64 v[10:11], v[4:5], 0, s[38:39]
	s_mov_b32 m0, s27
	s_add_i32 s25, s11, 0x6000
	v_lshl_add_u64 v[8:9], s[16:17], 0, v[40:41]
	global_load_lds_dwordx4 v[10:11], off
	v_lshl_add_u64 v[10:11], v[6:7], 0, s[38:39]
	s_mov_b32 m0, s25
	s_add_i32 s52, 0, 0x18000
	global_load_lds_dwordx4 v[10:11], off
	v_lshl_add_u64 v[10:11], v[8:9], 0, s[38:39]
	s_add_i32 m0, s27, 0x2000
	s_add_i32 s27, s11, 0x8000
	s_mov_b64 s[44:45], 0x100
	global_load_lds_dwordx4 v[10:11], off
	s_add_i32 s39, s52, s43
	v_lshl_add_u64 v[2:3], v[2:3], 0, s[44:45]
	s_mov_b32 m0, s27
	s_add_i32 s38, s11, 0xa000
	global_load_lds_dwordx4 v[2:3], off
	v_lshl_add_u64 v[2:3], v[4:5], 0, s[44:45]
	s_mov_b32 m0, s39
	s_sub_i32 s36, s36, s54
	global_load_lds_dwordx4 v[2:3], off
	v_lshl_add_u64 v[2:3], v[6:7], 0, s[44:45]
	s_mov_b32 m0, s38
	s_sub_i32 s36, s36, s53
	global_load_lds_dwordx4 v[2:3], off
	v_lshl_add_u64 v[2:3], v[8:9], 0, s[44:45]
	s_add_i32 m0, s39, 0x2000
	s_sext_i32_i16 s36, s36
	global_load_lds_dwordx4 v[2:3], off
	s_lshl_b32 s37, s37, 4
	s_lshl_b32 s36, s36, 1
	s_add_i32 s37, s37, s36
	s_or_b32 s54, s37, s55
	s_ashr_i32 s55, s54, 31
	s_add_i32 s39, s11, 0x1c000
	s_add_i32 s41, s11, 0x1e000
	v_add_u32_e32 v5, s50, v148
	s_add_i32 s43, s11, 0x10000
	s_add_i32 s44, s11, 0x12000
	v_add_u32_e32 v6, s51, v148
	s_add_i32 s45, s11, 0x14000
	s_add_i32 s50, s11, 0x16000
	v_add_u32_e32 v7, s52, v148
	s_add_i32 s51, s11, 0x18000
	s_add_i32 s52, s11, 0x1a000
	s_add_i32 s56, 0, 0x1c000
	s_lshl_b64 s[54:55], s[54:55], 20
	v_lshlrev_b32_e32 v2, 10, v0
	s_mov_b32 s36, 0x60000
	v_and_or_b32 v2, v2, s36, v13
	v_lshlrev_b32_e32 v9, 13, v12
	s_add_u32 s54, s30, s54
	v_or3_b32 v2, v2, v9, v14
	v_mov_b32_e32 v3, v35
	s_addc_u32 s55, s31, s55
	v_add_u32_e32 v8, s56, v148
	v_lshl_add_u64 v[2:3], s[54:55], 0, v[2:3]
	s_mov_b64 s[56:57], 0x20d00180
	v_lshl_add_u64 v[42:43], v[2:3], 0, s[56:57]
	v_lshlrev_b32_e32 v2, 6, v18
	s_mov_b32 s36, 0xe0000
	v_and_or_b32 v2, v2, s36, v13
	v_or3_b32 v2, v2, v9, v14
	v_mov_b32_e32 v3, v35
	v_lshl_add_u64 v[2:3], s[54:55], 0, v[2:3]
	v_lshl_add_u64 v[44:45], v[2:3], 0, s[56:57]
	v_or3_b32 v2, v17, v131, v16
	s_add_u32 s18, s30, s18
	v_lshl_or_b32 v2, v2, 13, v15
	v_mov_b32_e32 v3, v35
	s_addc_u32 s19, s31, s19
	v_lshl_add_u64 v[2:3], s[18:19], 0, v[2:3]
	s_mov_b64 s[54:55], 0xa500180
	v_lshl_add_u64 v[46:47], v[2:3], 0, s[54:55]
	v_or3_b32 v2, v19, v131, v16
	v_lshl_or_b32 v20, v163, 6, v149
	v_lshl_or_b32 v2, v2, 13, v15
	v_mov_b32_e32 v3, v35
	v_xad_u32 v4, v20, v21, 0
	v_lshl_add_u64 v[2:3], s[18:19], 0, v[2:3]
	v_lshl_add_u64 v[48:49], v[2:3], 0, s[54:55]
	s_mov_b32 s53, -4
	s_add_i32 s54, s11, 0xc000
	s_add_i32 s55, s11, 0xe000
	v_add_u32_e32 v50, s58, v4
	v_add_u32_e32 v51, s59, v5
	v_add_u32_e32 v52, s59, v6
	v_add_u32_e32 v53, s59, v7
	v_add_u32_e32 v54, s59, v8
	s_mov_b64 s[18:19], 0x200
	v_mov_b32_e32 v2, v35
	v_mov_b32_e32 v3, v35
	v_mov_b32_e32 v4, v35
	v_mov_b32_e32 v5, v35
	v_mov_b32_e32 v6, v35
	v_mov_b32_e32 v7, v35
	v_mov_b32_e32 v8, v35
	v_mov_b32_e32 v9, v35
	v_mov_b32_e32 v10, v35
	v_mov_b32_e32 v11, v35
	v_mov_b32_e32 v12, v35
	v_mov_b32_e32 v13, v35
	v_mov_b32_e32 v14, v35
	v_mov_b32_e32 v15, v35
	v_mov_b32_e32 v16, v35
	v_mov_b32_e32 v17, v35
	v_mov_b32_e32 v18, v35
	v_mov_b32_e32 v19, v35
	v_mov_b32_e32 v20, v35
	v_mov_b32_e32 v21, v35
	v_mov_b32_e32 v22, v35
	v_mov_b32_e32 v23, v35
	v_mov_b32_e32 v24, v35
	v_mov_b32_e32 v25, v35
	v_mov_b32_e32 v26, v35
	v_mov_b32_e32 v27, v35
	v_mov_b32_e32 v28, v35
	v_mov_b32_e32 v29, v35
	v_mov_b32_e32 v30, v35
	v_mov_b32_e32 v31, v35
	v_mov_b32_e32 v32, v35
	v_mov_b32_e32 v33, v35
	v_mov_b32_e32 v166, 0
	v_mov_b32_e32 v167, 0
	v_mov_b32_e32 v168, 0
	v_mov_b32_e32 v169, 0
	v_mov_b32_e32 v170, 0
	v_mov_b32_e32 v171, 0
	v_mov_b32_e32 v172, 0
	v_mov_b32_e32 v173, 0
	v_mov_b32_e32 v202, 0
	v_mov_b32_e32 v203, 0
	v_mov_b32_e32 v204, 0
	v_mov_b32_e32 v205, 0
	v_mov_b32_e32 v206, 0
	v_mov_b32_e32 v207, 0
	v_mov_b32_e32 v208, 0
	v_mov_b32_e32 v209, 0
	v_mov_b32_e32 v210, 0
	v_mov_b32_e32 v211, 0
	v_mov_b32_e32 v212, 0
	v_mov_b32_e32 v213, 0
	v_mov_b32_e32 v214, 0
	v_mov_b32_e32 v215, 0
	v_mov_b32_e32 v216, 0
	v_mov_b32_e32 v217, 0
	v_mov_b32_e32 v218, 0
	v_mov_b32_e32 v219, 0
	v_mov_b32_e32 v220, 0
	v_mov_b32_e32 v221, 0
	v_mov_b32_e32 v222, 0
	v_mov_b32_e32 v223, 0
	v_mov_b32_e32 v224, 0
	v_mov_b32_e32 v225, 0
	v_mov_b32_e32 v226, 0
	v_mov_b32_e32 v227, 0
	v_mov_b32_e32 v228, 0
	v_mov_b32_e32 v229, 0
	v_mov_b32_e32 v230, 0
	v_mov_b32_e32 v231, 0
	v_mov_b32_e32 v232, 0
	v_mov_b32_e32 v233, 0
	v_mov_b32_e32 v234, 0
	v_mov_b32_e32 v235, 0
	v_mov_b32_e32 v236, 0
	v_mov_b32_e32 v237, 0
	v_mov_b32_e32 v238, 0
	v_mov_b32_e32 v239, 0
	v_mov_b32_e32 v240, 0
	v_mov_b32_e32 v241, 0
.LBB0_1712:
	s_mov_b32 m0, s54
	s_waitcnt lgkmcnt(0)
	s_waitcnt vmcnt(8)
	s_barrier
	ds_read_b128 v[56:59], v50
	ds_read_b128 v[60:63], v50 offset:1024
	ds_read_b128 v[64:67], v50 offset:2048
	ds_read_b128 v[68:71], v50 offset:3072
	ds_read_b128 v[72:75], v50 offset:4096
	ds_read_b128 v[76:79], v50 offset:5120
	ds_read_b128 v[80:83], v50 offset:6144
	ds_read_b128 v[84:87], v50 offset:7168
	ds_read_b128 v[88:91], v51
	ds_read_b128 v[92:95], v51 offset:1024
	ds_read_b128 v[96:99], v51 offset:2048
	ds_read_b128 v[100:103], v51 offset:3072
	s_setprio 1
	v_mfma_f32_16x16x32_bf16 v[30:33], v[234:237], v[202:205], v[30:33]
	v_mfma_f32_16x16x32_bf16 v[26:29], v[166:169], v[202:205], v[26:29]
	v_mfma_f32_16x16x32_bf16 v[22:25], v[234:237], v[210:213], v[22:25]
	v_mfma_f32_16x16x32_bf16 v[18:21], v[166:169], v[210:213], v[18:21]
	global_load_lds_dwordx4 v[42:43], off
	v_mfma_f32_16x16x32_bf16 v[14:17], v[234:237], v[218:221], v[14:17]
	v_mfma_f32_16x16x32_bf16 v[10:13], v[166:169], v[218:221], v[10:13]
	v_mfma_f32_16x16x32_bf16 v[6:9], v[234:237], v[226:229], v[6:9]
	v_mfma_f32_16x16x32_bf16 v[2:5], v[166:169], v[226:229], v[2:5]
	s_mov_b32 m0, s39
	s_add_i32 s36, s53, 7
	global_load_lds_dwordx4 v[46:47], off
	v_mfma_f32_16x16x32_bf16 v[30:33], v[238:241], v[206:209], v[30:33]
	v_mfma_f32_16x16x32_bf16 v[26:29], v[170:173], v[206:209], v[26:29]
	v_mfma_f32_16x16x32_bf16 v[22:25], v[238:241], v[214:217], v[22:25]
	v_mfma_f32_16x16x32_bf16 v[18:21], v[170:173], v[214:217], v[18:21]
	s_mov_b32 m0, s55
	s_nop 0
	global_load_lds_dwordx4 v[44:45], off
	v_mfma_f32_16x16x32_bf16 v[14:17], v[238:241], v[222:225], v[14:17]
	v_mfma_f32_16x16x32_bf16 v[10:13], v[170:173], v[222:225], v[10:13]
	v_mfma_f32_16x16x32_bf16 v[6:9], v[238:241], v[230:233], v[6:9]
	v_mfma_f32_16x16x32_bf16 v[2:5], v[170:173], v[230:233], v[2:5]
	s_mov_b32 m0, s41
	s_nop 0
	global_load_lds_dwordx4 v[48:49], off
	s_setprio 0
	s_add_i32 s37, s53, 5
	s_cmp_lt_u32 s37, 61
	s_cselect_b32 s56, 3, 0xffffffc3
	s_add_i32 s56, s37, s56
	s_ashr_i32 s57, s56, 31
	s_lshl_b64 s[56:57], s[56:57], 7
	s_add_u32 s58, s14, s56
	s_addc_u32 s59, s15, s57
	s_add_u32 s56, s16, s56
	s_mov_b32 m0, s11
	s_addc_u32 s57, s17, s57
	v_lshl_add_u64 v[104:105], s[58:59], 0, v[34:35]
	s_waitcnt lgkmcnt(0)
	s_waitcnt vmcnt(8)
	s_barrier
	ds_read_b128 v[202:205], v50 offset:16384
	ds_read_b128 v[206:209], v50 offset:17408
	ds_read_b128 v[210:213], v50 offset:18432
	ds_read_b128 v[214:217], v50 offset:19456
	ds_read_b128 v[218:221], v50 offset:20480
	ds_read_b128 v[222:225], v50 offset:21504
	ds_read_b128 v[226:229], v50 offset:22528
	ds_read_b128 v[230:233], v50 offset:23552
	ds_read_b128 v[234:237], v52
	ds_read_b128 v[238:241], v52 offset:1024
	ds_read_b128 v[166:169], v52 offset:2048
	ds_read_b128 v[170:173], v52 offset:3072
	s_setprio 1
	v_mfma_f32_16x16x32_bf16 v[30:33], v[88:91], v[56:59], v[30:33]
	v_mfma_f32_16x16x32_bf16 v[26:29], v[96:99], v[56:59], v[26:29]
	v_mfma_f32_16x16x32_bf16 v[22:25], v[88:91], v[64:67], v[22:25]
	v_mfma_f32_16x16x32_bf16 v[18:21], v[96:99], v[64:67], v[18:21]
	global_load_lds_dwordx4 v[104:105], off
	v_mfma_f32_16x16x32_bf16 v[14:17], v[88:91], v[72:75], v[14:17]
	v_mfma_f32_16x16x32_bf16 v[10:13], v[96:99], v[72:75], v[10:13]
	v_mfma_f32_16x16x32_bf16 v[6:9], v[88:91], v[80:83], v[6:9]
	v_mfma_f32_16x16x32_bf16 v[2:5], v[96:99], v[80:83], v[2:5]
	v_lshl_add_u64 v[104:105], s[56:57], 0, v[36:37]
	s_mov_b32 m0, s43
	s_nop 0
	global_load_lds_dwordx4 v[104:105], off
	v_mfma_f32_16x16x32_bf16 v[30:33], v[92:95], v[60:63], v[30:33]
	v_mfma_f32_16x16x32_bf16 v[26:29], v[100:103], v[60:63], v[26:29]
	v_mfma_f32_16x16x32_bf16 v[22:25], v[92:95], v[68:71], v[22:25]
	v_mfma_f32_16x16x32_bf16 v[18:21], v[100:103], v[68:71], v[18:21]
	v_lshl_add_u64 v[104:105], s[58:59], 0, v[38:39]
	s_mov_b32 m0, s21
	s_nop 0
	global_load_lds_dwordx4 v[104:105], off
	v_mfma_f32_16x16x32_bf16 v[14:17], v[92:95], v[76:79], v[14:17]
	v_mfma_f32_16x16x32_bf16 v[10:13], v[100:103], v[76:79], v[10:13]
	v_mfma_f32_16x16x32_bf16 v[6:9], v[92:95], v[84:87], v[6:9]
	v_mfma_f32_16x16x32_bf16 v[2:5], v[100:103], v[84:87], v[2:5]
	v_lshl_add_u64 v[104:105], s[56:57], 0, v[40:41]
	s_mov_b32 m0, s44
	s_nop 0
	global_load_lds_dwordx4 v[104:105], off
	s_setprio 0
	s_add_i32 s37, s53, 6
	s_cmp_lt_u32 s37, 61
	s_cselect_b32 s56, 3, 0xffffffc3
	s_add_i32 s56, s37, s56
	s_ashr_i32 s57, s56, 31
	s_lshl_b64 s[56:57], s[56:57], 7
	s_add_u32 s58, s14, s56
	s_addc_u32 s59, s15, s57
	s_add_u32 s56, s16, s56
	s_mov_b32 m0, s24
	s_addc_u32 s57, s17, s57
	v_lshl_add_u64 v[104:105], s[58:59], 0, v[34:35]
	s_waitcnt lgkmcnt(0)
	s_waitcnt vmcnt(8)
	s_barrier
	ds_read_b128 v[56:59], v50 offset:32768
	ds_read_b128 v[60:63], v50 offset:33792
	ds_read_b128 v[64:67], v50 offset:34816
	ds_read_b128 v[68:71], v50 offset:35840
	ds_read_b128 v[72:75], v50 offset:36864
	ds_read_b128 v[76:79], v50 offset:37888
	ds_read_b128 v[80:83], v50 offset:38912
	ds_read_b128 v[84:87], v50 offset:39936
	ds_read_b128 v[88:91], v53
	ds_read_b128 v[92:95], v53 offset:1024
	ds_read_b128 v[96:99], v53 offset:2048
	ds_read_b128 v[100:103], v53 offset:3072
	s_setprio 1
	v_mfma_f32_16x16x32_bf16 v[30:33], v[234:237], v[202:205], v[30:33]
	v_mfma_f32_16x16x32_bf16 v[26:29], v[166:169], v[202:205], v[26:29]
	v_mfma_f32_16x16x32_bf16 v[22:25], v[234:237], v[210:213], v[22:25]
	v_mfma_f32_16x16x32_bf16 v[18:21], v[166:169], v[210:213], v[18:21]
	global_load_lds_dwordx4 v[104:105], off
	v_mfma_f32_16x16x32_bf16 v[14:17], v[234:237], v[218:221], v[14:17]
	v_mfma_f32_16x16x32_bf16 v[10:13], v[166:169], v[218:221], v[10:13]
	v_mfma_f32_16x16x32_bf16 v[6:9], v[234:237], v[226:229], v[6:9]
	v_mfma_f32_16x16x32_bf16 v[2:5], v[166:169], v[226:229], v[2:5]
	v_lshl_add_u64 v[104:105], s[56:57], 0, v[36:37]
	s_mov_b32 m0, s45
	s_nop 0
	global_load_lds_dwordx4 v[104:105], off
	v_mfma_f32_16x16x32_bf16 v[30:33], v[238:241], v[206:209], v[30:33]
	v_mfma_f32_16x16x32_bf16 v[26:29], v[170:173], v[206:209], v[26:29]
	v_mfma_f32_16x16x32_bf16 v[22:25], v[238:241], v[214:217], v[22:25]
	v_mfma_f32_16x16x32_bf16 v[18:21], v[170:173], v[214:217], v[18:21]
	v_lshl_add_u64 v[104:105], s[58:59], 0, v[38:39]
	s_mov_b32 m0, s25
	s_nop 0
	global_load_lds_dwordx4 v[104:105], off
	v_mfma_f32_16x16x32_bf16 v[14:17], v[238:241], v[222:225], v[14:17]
	v_mfma_f32_16x16x32_bf16 v[10:13], v[170:173], v[222:225], v[10:13]
	v_mfma_f32_16x16x32_bf16 v[6:9], v[238:241], v[230:233], v[6:9]
	v_mfma_f32_16x16x32_bf16 v[2:5], v[170:173], v[230:233], v[2:5]
	v_lshl_add_u64 v[104:105], s[56:57], 0, v[40:41]
	s_mov_b32 m0, s50
	s_nop 0
	global_load_lds_dwordx4 v[104:105], off
	s_setprio 0
	s_cmp_lt_u32 s36, 61
	s_cselect_b32 s37, 3, 0xffffffc3
	s_add_i32 s56, s36, s37
	s_ashr_i32 s57, s56, 31
	s_lshl_b64 s[56:57], s[56:57], 7
	s_add_u32 s58, s14, s56
	s_addc_u32 s59, s15, s57
	s_add_u32 s56, s16, s56
	s_mov_b32 m0, s27
	s_addc_u32 s57, s17, s57
	v_lshl_add_u64 v[104:105], s[58:59], 0, v[34:35]
	s_waitcnt lgkmcnt(0)
	s_waitcnt vmcnt(8)
	s_barrier
	ds_read_b128 v[202:205], v50 offset:49152
	ds_read_b128 v[206:209], v50 offset:50176
	ds_read_b128 v[210:213], v50 offset:51200
	ds_read_b128 v[214:217], v50 offset:52224
	ds_read_b128 v[218:221], v50 offset:53248
	ds_read_b128 v[222:225], v50 offset:54272
	ds_read_b128 v[226:229], v50 offset:55296
	ds_read_b128 v[230:233], v50 offset:56320
	ds_read_b128 v[234:237], v54
	ds_read_b128 v[238:241], v54 offset:1024
	ds_read_b128 v[166:169], v54 offset:2048
	ds_read_b128 v[170:173], v54 offset:3072
	s_setprio 1
	v_mfma_f32_16x16x32_bf16 v[30:33], v[88:91], v[56:59], v[30:33]
	v_mfma_f32_16x16x32_bf16 v[26:29], v[96:99], v[56:59], v[26:29]
	v_mfma_f32_16x16x32_bf16 v[22:25], v[88:91], v[64:67], v[22:25]
	v_mfma_f32_16x16x32_bf16 v[18:21], v[96:99], v[64:67], v[18:21]
	global_load_lds_dwordx4 v[104:105], off
	v_mfma_f32_16x16x32_bf16 v[14:17], v[88:91], v[72:75], v[14:17]
	v_mfma_f32_16x16x32_bf16 v[10:13], v[96:99], v[72:75], v[10:13]
	v_mfma_f32_16x16x32_bf16 v[6:9], v[88:91], v[80:83], v[6:9]
	v_mfma_f32_16x16x32_bf16 v[2:5], v[96:99], v[80:83], v[2:5]
	v_lshl_add_u64 v[104:105], s[56:57], 0, v[36:37]
	s_mov_b32 m0, s51
	s_nop 0
	global_load_lds_dwordx4 v[104:105], off
	v_mfma_f32_16x16x32_bf16 v[30:33], v[92:95], v[60:63], v[30:33]
	v_mfma_f32_16x16x32_bf16 v[26:29], v[100:103], v[60:63], v[26:29]
	v_mfma_f32_16x16x32_bf16 v[22:25], v[92:95], v[68:71], v[22:25]
	v_mfma_f32_16x16x32_bf16 v[18:21], v[100:103], v[68:71], v[18:21]
	v_lshl_add_u64 v[104:105], s[58:59], 0, v[38:39]
	s_mov_b32 m0, s38
	s_nop 0
	global_load_lds_dwordx4 v[104:105], off
	v_mfma_f32_16x16x32_bf16 v[14:17], v[92:95], v[76:79], v[14:17]
	v_mfma_f32_16x16x32_bf16 v[10:13], v[100:103], v[76:79], v[10:13]
	v_mfma_f32_16x16x32_bf16 v[6:9], v[92:95], v[84:87], v[6:9]
	v_mfma_f32_16x16x32_bf16 v[2:5], v[100:103], v[84:87], v[2:5]
	v_lshl_add_u64 v[104:105], s[56:57], 0, v[40:41]
	s_mov_b32 m0, s52
	s_nop 0
	global_load_lds_dwordx4 v[104:105], off
	s_setprio 0
	s_add_i32 s53, s53, 4
	v_lshl_add_u64 v[42:43], v[42:43], 0, s[18:19]
	v_lshl_add_u64 v[44:45], v[44:45], 0, s[18:19]
	v_lshl_add_u64 v[46:47], v[46:47], 0, s[18:19]
	s_cmp_lt_u32 s53, 60
	v_lshl_add_u64 v[48:49], v[48:49], 0, s[18:19]
	s_cbranch_scc1 .LBB0_1712
	s_waitcnt lgkmcnt(0)
	s_setprio 1
	v_mfma_f32_16x16x32_bf16 v[30:33], v[234:237], v[202:205], v[30:33]
	v_mfma_f32_16x16x32_bf16 v[26:29], v[166:169], v[202:205], v[26:29]
	v_mfma_f32_16x16x32_bf16 v[22:25], v[234:237], v[210:213], v[22:25]
	v_mfma_f32_16x16x32_bf16 v[18:21], v[166:169], v[210:213], v[18:21]
	v_mfma_f32_16x16x32_bf16 v[14:17], v[234:237], v[218:221], v[14:17]
	v_mfma_f32_16x16x32_bf16 v[10:13], v[166:169], v[218:221], v[10:13]
	v_mfma_f32_16x16x32_bf16 v[6:9], v[234:237], v[226:229], v[6:9]
	v_mfma_f32_16x16x32_bf16 v[2:5], v[166:169], v[226:229], v[2:5]
	v_mfma_f32_16x16x32_bf16 v[30:33], v[238:241], v[206:209], v[30:33]
	v_mfma_f32_16x16x32_bf16 v[26:29], v[170:173], v[206:209], v[26:29]
	v_mfma_f32_16x16x32_bf16 v[22:25], v[238:241], v[214:217], v[22:25]
	v_mfma_f32_16x16x32_bf16 v[18:21], v[170:173], v[214:217], v[18:21]
	v_mfma_f32_16x16x32_bf16 v[14:17], v[238:241], v[222:225], v[14:17]
	v_mfma_f32_16x16x32_bf16 v[10:13], v[170:173], v[222:225], v[10:13]
	v_mfma_f32_16x16x32_bf16 v[6:9], v[238:241], v[230:233], v[6:9]
	v_mfma_f32_16x16x32_bf16 v[2:5], v[170:173], v[230:233], v[2:5]
	s_setprio 0
	s_lshl_b32 s10, s10, 7
	s_or_b32 s5, s5, s10
	s_lshl_b32 s4, s4, 7
	v_or_b32_e32 v34, s5, v131
	s_add_i32 s4, s4, s20
	v_ashrrev_i32_e32 v35, 31, v34
	v_or_b32_e32 v36, s4, v163
	v_lshl_add_u64 v[34:35], v[34:35], 1, s[46:47]
	s_mov_b32 s10, 0xac00
	s_waitcnt vmcnt(0)
	s_barrier
	v_cvt_pk_bf16_f32 v30, v30, v31
	v_cvt_pk_bf16_f32 v31, v32, v33
	v_cvt_pk_bf16_f32 v32, v26, v27
	v_mad_i64_i32 v[26:27], s[4:5], v36, s10, v[34:35]
	v_cvt_pk_bf16_f32 v33, v28, v29
	global_store_dwordx4 v[26:27], v[30:33], off nt
	v_or_b32_e32 v26, 16, v36
	v_cvt_pk_bf16_f32 v22, v22, v23
	v_cvt_pk_bf16_f32 v23, v24, v25
	v_cvt_pk_bf16_f32 v24, v18, v19
	v_mad_i64_i32 v[18:19], s[4:5], v26, s10, v[34:35]
	v_cvt_pk_bf16_f32 v25, v20, v21
	global_store_dwordx4 v[18:19], v[22:25], off nt
	v_or_b32_e32 v18, 32, v36
	v_cvt_pk_bf16_f32 v14, v14, v15
	v_cvt_pk_bf16_f32 v15, v16, v17
	v_cvt_pk_bf16_f32 v16, v10, v11
	v_mad_i64_i32 v[10:11], s[4:5], v18, s10, v[34:35]
	v_cvt_pk_bf16_f32 v17, v12, v13
	global_store_dwordx4 v[10:11], v[14:17], off nt
	v_or_b32_e32 v10, 48, v36
	v_cvt_pk_bf16_f32 v6, v6, v7
	v_cvt_pk_bf16_f32 v7, v8, v9
	v_cvt_pk_bf16_f32 v8, v2, v3
	v_mad_i64_i32 v[2:3], s[4:5], v10, s10, v[34:35]
	v_cvt_pk_bf16_f32 v9, v4, v5
	global_store_dwordx4 v[2:3], v[6:9], off nt

.LBB0_2165:
	s_lshl_b32 s0, s2, 2
	s_bfe_u32 s26, s2, 0x30003
	s_and_b32 s0, s0, 28
	s_ashr_i32 s1, s2, 6
	v_readfirstlane_b32 s2, v0
	s_add_i32 s0, s0, s1
	s_lshr_b32 s1, s2, 2
	s_and_b32 s9, s1, 0x3fffffc0
	s_ashr_i32 s1, s0, 31
	s_lshr_b32 s4, s2, 1
	s_lshl_b64 s[24:25], s[0:1], 20
	s_lshl_b32 s1, s2, 4
	s_or_b32 s8, s26, 64
	s_and_b32 s16, s1, 0xfffffc00
	s_and_b32 s1, s4, 0x60
	s_lshl_b32 s5, s8, 20
	s_lshl_b32 s38, s9, 7
	s_lshl_b32 s39, s1, 7
	s_add_u32 s2, s3, s5
	s_addc_u32 s3, s33, 0
	s_add_u32 s4, s36, s24
	s_addc_u32 s5, s37, s25
	s_add_i32 s10, s16, 0
	s_add_i32 s18, 0, 0x10000
	s_add_i32 s12, s18, s16
	v_lshl_add_u64 v[2:3], s[2:3], 0, v[130:131]
	s_mov_b32 m0, s10
	v_lshl_add_u64 v[4:5], s[4:5], 0, v[132:133]
	global_load_lds_dwordx4 v[2:3], off
	s_mov_b32 m0, s12
	s_add_i32 s11, s10, 0x2000
	global_load_lds_dwordx4 v[4:5], off
	v_lshl_add_u64 v[6:7], s[2:3], 0, v[136:137]
	s_mov_b32 m0, s11
	v_lshl_add_u64 v[8:9], s[4:5], 0, v[134:135]
	global_load_lds_dwordx4 v[6:7], off
	s_add_i32 m0, s12, 0x2000
	s_add_i32 s12, s10, 0x4000
	s_add_i32 s20, 0, 0x14000
	s_mov_b64 s[14:15], 0x80
	global_load_lds_dwordx4 v[8:9], off
	s_add_i32 s17, s20, s16
	v_lshl_add_u64 v[10:11], v[2:3], 0, s[14:15]
	s_mov_b32 m0, s12
	s_add_i32 s13, s10, 0x6000
	global_load_lds_dwordx4 v[10:11], off
	v_lshl_add_u64 v[10:11], v[4:5], 0, s[14:15]
	s_mov_b32 m0, s17
	s_add_i32 s22, 0, 0x18000
	global_load_lds_dwordx4 v[10:11], off
	v_lshl_add_u64 v[10:11], v[6:7], 0, s[14:15]
	s_mov_b32 m0, s13
	s_add_i32 s19, s22, s16
	global_load_lds_dwordx4 v[10:11], off
	v_lshl_add_u64 v[10:11], v[8:9], 0, s[14:15]
	s_add_i32 m0, s17, 0x2000
	s_add_i32 s14, s10, 0x8000
	s_mov_b64 s[16:17], 0x100
	global_load_lds_dwordx4 v[10:11], off
	v_lshl_add_u64 v[2:3], v[2:3], 0, s[16:17]
	s_mov_b32 m0, s14
	s_add_i32 s15, s10, 0xa000
	global_load_lds_dwordx4 v[2:3], off
	v_lshl_add_u64 v[2:3], v[4:5], 0, s[16:17]
	s_mov_b32 m0, s19
	v_lshl_or_b32 v0, v163, 6, v153
	global_load_lds_dwordx4 v[2:3], off
	v_lshl_add_u64 v[2:3], v[6:7], 0, s[16:17]
	s_mov_b32 m0, s15
	s_mov_b32 s27, 0
	global_load_lds_dwordx4 v[2:3], off
	v_lshl_add_u64 v[2:3], v[8:9], 0, s[16:17]
	s_add_i32 m0, s19, 0x2000
	s_add_i32 s33, 0, 0x1c000
	global_load_lds_dwordx4 v[2:3], off
	v_lshlrev_b32_e32 v2, 2, v163
	v_and_b32_e32 v2, 32, v2
	s_lshl_b32 s26, s26, 20
	v_xad_u32 v2, v0, v2, 0
	v_add_u32_e32 v3, s18, v1
	v_add_u32_e32 v4, s20, v1
	v_add_u32_e32 v5, s22, v1
	v_add_u32_e32 v6, s33, v1
	v_lshl_add_u64 v[0:1], v[130:131], 0, s[26:27]
	s_mov_b64 s[34:35], 0x24d00180
	v_lshl_add_u64 v[32:33], v[0:1], 0, s[34:35]
	v_lshl_add_u64 v[0:1], v[136:137], 0, s[26:27]
	v_lshl_add_u64 v[34:35], v[0:1], 0, s[34:35]
	v_lshl_add_u64 v[0:1], v[132:133], 0, s[24:25]
	s_mov_b64 s[26:27], 0x1c700180
	v_lshl_add_u64 v[36:37], v[0:1], 0, s[26:27]
	v_lshl_add_u64 v[0:1], v[134:135], 0, s[24:25]
	v_lshl_add_u64 v[38:39], v[0:1], 0, s[26:27]
	v_mov_b32_e32 v0, 0
	s_add_i32 s16, s10, 0x1c000
	s_add_i32 s17, s10, 0x1e000
	s_add_i32 s18, s10, 0x10000
	s_add_i32 s19, s10, 0x12000
	s_add_i32 s20, s10, 0x14000
	s_add_i32 s21, s10, 0x16000
	s_add_i32 s22, s10, 0x18000
	s_add_i32 s23, s10, 0x1a000
	s_mov_b32 s24, -4
	s_add_i32 s25, s10, 0xc000
	s_add_i32 s26, s10, 0xe000
	v_add_u32_e32 v40, s38, v2
	v_add_u32_e32 v41, s39, v3
	s_waitcnt lgkmcnt(0)
	v_add_u32_e32 v42, s39, v4
	v_add_u32_e32 v43, s39, v5
	v_add_u32_e32 v44, s39, v6
	v_mov_b32_e32 v1, v0
	v_mov_b32_e32 v2, v0
	v_mov_b32_e32 v3, v0
	v_mov_b32_e32 v4, v0
	v_mov_b32_e32 v5, v0
	v_mov_b32_e32 v6, v0
	v_mov_b32_e32 v7, v0
	v_mov_b32_e32 v8, v0
	v_mov_b32_e32 v9, v0
	v_mov_b32_e32 v10, v0
	v_mov_b32_e32 v11, v0
	v_mov_b32_e32 v12, v0
	v_mov_b32_e32 v13, v0
	v_mov_b32_e32 v14, v0
	v_mov_b32_e32 v15, v0
	v_mov_b32_e32 v16, v0
	v_mov_b32_e32 v17, v0
	v_mov_b32_e32 v18, v0
	v_mov_b32_e32 v19, v0
	v_mov_b32_e32 v20, v0
	v_mov_b32_e32 v21, v0
	v_mov_b32_e32 v22, v0
	v_mov_b32_e32 v23, v0
	v_mov_b32_e32 v24, v0
	v_mov_b32_e32 v25, v0
	v_mov_b32_e32 v26, v0
	v_mov_b32_e32 v27, v0
	v_mov_b32_e32 v28, v0
	v_mov_b32_e32 v29, v0
	v_mov_b32_e32 v30, v0
	v_mov_b32_e32 v31, v0
	v_mov_b32_e32 v166, 0
	v_mov_b32_e32 v167, 0
	v_mov_b32_e32 v168, 0
	v_mov_b32_e32 v169, 0
	v_mov_b32_e32 v170, 0
	v_mov_b32_e32 v171, 0
	v_mov_b32_e32 v172, 0
	v_mov_b32_e32 v173, 0
	v_mov_b32_e32 v202, 0
	v_mov_b32_e32 v203, 0
	v_mov_b32_e32 v204, 0
	v_mov_b32_e32 v205, 0
	v_mov_b32_e32 v206, 0
	v_mov_b32_e32 v207, 0
	v_mov_b32_e32 v208, 0
	v_mov_b32_e32 v209, 0
	v_mov_b32_e32 v210, 0
	v_mov_b32_e32 v211, 0
	v_mov_b32_e32 v212, 0
	v_mov_b32_e32 v213, 0
	v_mov_b32_e32 v214, 0
	v_mov_b32_e32 v215, 0
	v_mov_b32_e32 v216, 0
	v_mov_b32_e32 v217, 0
	v_mov_b32_e32 v218, 0
	v_mov_b32_e32 v219, 0
	v_mov_b32_e32 v220, 0
	v_mov_b32_e32 v221, 0
	v_mov_b32_e32 v222, 0
	v_mov_b32_e32 v223, 0
	v_mov_b32_e32 v224, 0
	v_mov_b32_e32 v225, 0
	v_mov_b32_e32 v226, 0
	v_mov_b32_e32 v227, 0
	v_mov_b32_e32 v228, 0
	v_mov_b32_e32 v229, 0
	v_mov_b32_e32 v230, 0
	v_mov_b32_e32 v231, 0
	v_mov_b32_e32 v232, 0
	v_mov_b32_e32 v233, 0
	v_mov_b32_e32 v234, 0
	v_mov_b32_e32 v235, 0
	v_mov_b32_e32 v236, 0
	v_mov_b32_e32 v237, 0
	v_mov_b32_e32 v238, 0
	v_mov_b32_e32 v239, 0
	v_mov_b32_e32 v240, 0
	v_mov_b32_e32 v241, 0
.LBB0_2166:
	s_mov_b32 m0, s25
	v_lshl_add_u64 v[104:105], s[30:31], 0, v[32:33]
	s_waitcnt lgkmcnt(0)
	s_waitcnt vmcnt(8)
	s_barrier
	ds_read_b128 v[46:49], v40
	ds_read_b128 v[50:53], v40 offset:1024
	ds_read_b128 v[54:57], v40 offset:2048
	ds_read_b128 v[58:61], v40 offset:3072
	ds_read_b128 v[62:65], v40 offset:4096
	ds_read_b128 v[66:69], v40 offset:5120
	ds_read_b128 v[70:73], v40 offset:6144
	ds_read_b128 v[74:77], v40 offset:7168
	ds_read_b128 v[78:81], v41
	ds_read_b128 v[82:85], v41 offset:1024
	ds_read_b128 v[86:89], v41 offset:2048
	ds_read_b128 v[90:93], v41 offset:3072
	s_setprio 1
	v_mfma_f32_16x16x32_bf16 v[28:31], v[234:237], v[202:205], v[28:31]
	v_mfma_f32_16x16x32_bf16 v[24:27], v[166:169], v[202:205], v[24:27]
	v_mfma_f32_16x16x32_bf16 v[20:23], v[234:237], v[210:213], v[20:23]
	v_mfma_f32_16x16x32_bf16 v[16:19], v[166:169], v[210:213], v[16:19]
	global_load_lds_dwordx4 v[104:105], off
	v_mfma_f32_16x16x32_bf16 v[12:15], v[234:237], v[218:221], v[12:15]
	v_mfma_f32_16x16x32_bf16 v[8:11], v[166:169], v[218:221], v[8:11]
	v_mfma_f32_16x16x32_bf16 v[4:7], v[234:237], v[226:229], v[4:7]
	v_mfma_f32_16x16x32_bf16 v[0:3], v[166:169], v[226:229], v[0:3]
	v_lshl_add_u64 v[104:105], s[30:31], 0, v[36:37]
	s_mov_b32 m0, s16
	s_add_i32 s27, s24, 7
	global_load_lds_dwordx4 v[104:105], off
	v_mfma_f32_16x16x32_bf16 v[28:31], v[238:241], v[206:209], v[28:31]
	v_mfma_f32_16x16x32_bf16 v[24:27], v[170:173], v[206:209], v[24:27]
	v_mfma_f32_16x16x32_bf16 v[20:23], v[238:241], v[214:217], v[20:23]
	v_mfma_f32_16x16x32_bf16 v[16:19], v[170:173], v[214:217], v[16:19]
	v_lshl_add_u64 v[104:105], s[30:31], 0, v[34:35]
	s_mov_b32 m0, s26
	s_nop 0
	global_load_lds_dwordx4 v[104:105], off
	v_mfma_f32_16x16x32_bf16 v[12:15], v[238:241], v[222:225], v[12:15]
	v_mfma_f32_16x16x32_bf16 v[8:11], v[170:173], v[222:225], v[8:11]
	v_mfma_f32_16x16x32_bf16 v[4:7], v[238:241], v[230:233], v[4:7]
	v_mfma_f32_16x16x32_bf16 v[0:3], v[170:173], v[230:233], v[0:3]
	v_lshl_add_u64 v[104:105], s[30:31], 0, v[38:39]
	s_mov_b32 m0, s17
	s_nop 0
	global_load_lds_dwordx4 v[104:105], off
	s_setprio 0
	s_add_i32 s33, s24, 5
	s_cmp_lt_u32 s33, 61
	s_cselect_b32 s34, 3, 0xffffffc3
	s_add_i32 s34, s33, s34
	s_ashr_i32 s35, s34, 31
	s_lshl_b64 s[34:35], s[34:35], 7
	s_add_u32 s36, s2, s34
	s_addc_u32 s37, s3, s35
	s_add_u32 s34, s4, s34
	s_mov_b32 m0, s10
	s_addc_u32 s35, s5, s35
	v_lshl_add_u64 v[104:105], s[36:37], 0, v[130:131]
	s_waitcnt lgkmcnt(0)
	s_waitcnt vmcnt(8)
	s_barrier
	ds_read_b128 v[202:205], v40 offset:16384
	ds_read_b128 v[206:209], v40 offset:17408
	ds_read_b128 v[210:213], v40 offset:18432
	ds_read_b128 v[214:217], v40 offset:19456
	ds_read_b128 v[218:221], v40 offset:20480
	ds_read_b128 v[222:225], v40 offset:21504
	ds_read_b128 v[226:229], v40 offset:22528
	ds_read_b128 v[230:233], v40 offset:23552
	ds_read_b128 v[234:237], v42
	ds_read_b128 v[238:241], v42 offset:1024
	ds_read_b128 v[166:169], v42 offset:2048
	ds_read_b128 v[170:173], v42 offset:3072
	s_setprio 1
	v_mfma_f32_16x16x32_bf16 v[28:31], v[78:81], v[46:49], v[28:31]
	v_mfma_f32_16x16x32_bf16 v[24:27], v[86:89], v[46:49], v[24:27]
	v_mfma_f32_16x16x32_bf16 v[20:23], v[78:81], v[54:57], v[20:23]
	v_mfma_f32_16x16x32_bf16 v[16:19], v[86:89], v[54:57], v[16:19]
	global_load_lds_dwordx4 v[104:105], off
	v_mfma_f32_16x16x32_bf16 v[12:15], v[78:81], v[62:65], v[12:15]
	v_mfma_f32_16x16x32_bf16 v[8:11], v[86:89], v[62:65], v[8:11]
	v_mfma_f32_16x16x32_bf16 v[4:7], v[78:81], v[70:73], v[4:7]
	v_mfma_f32_16x16x32_bf16 v[0:3], v[86:89], v[70:73], v[0:3]
	v_lshl_add_u64 v[104:105], s[34:35], 0, v[132:133]
	s_mov_b32 m0, s18
	s_nop 0
	global_load_lds_dwordx4 v[104:105], off
	v_mfma_f32_16x16x32_bf16 v[28:31], v[82:85], v[50:53], v[28:31]
	v_mfma_f32_16x16x32_bf16 v[24:27], v[90:93], v[50:53], v[24:27]
	v_mfma_f32_16x16x32_bf16 v[20:23], v[82:85], v[58:61], v[20:23]
	v_mfma_f32_16x16x32_bf16 v[16:19], v[90:93], v[58:61], v[16:19]
	v_lshl_add_u64 v[104:105], s[36:37], 0, v[136:137]
	s_mov_b32 m0, s11
	s_nop 0
	global_load_lds_dwordx4 v[104:105], off
	v_mfma_f32_16x16x32_bf16 v[12:15], v[82:85], v[66:69], v[12:15]
	v_mfma_f32_16x16x32_bf16 v[8:11], v[90:93], v[66:69], v[8:11]
	v_mfma_f32_16x16x32_bf16 v[4:7], v[82:85], v[74:77], v[4:7]
	v_mfma_f32_16x16x32_bf16 v[0:3], v[90:93], v[74:77], v[0:3]
	v_lshl_add_u64 v[104:105], s[34:35], 0, v[134:135]
	s_mov_b32 m0, s19
	s_nop 0
	global_load_lds_dwordx4 v[104:105], off
	s_setprio 0
	s_add_i32 s33, s24, 6
	s_cmp_lt_u32 s33, 61
	s_cselect_b32 s34, 3, 0xffffffc3
	s_add_i32 s34, s33, s34
	s_ashr_i32 s35, s34, 31
	s_lshl_b64 s[34:35], s[34:35], 7
	s_add_u32 s36, s2, s34
	s_addc_u32 s37, s3, s35
	s_add_u32 s34, s4, s34
	s_mov_b32 m0, s12
	s_addc_u32 s35, s5, s35
	v_lshl_add_u64 v[104:105], s[36:37], 0, v[130:131]
	s_waitcnt lgkmcnt(0)
	s_waitcnt vmcnt(8)
	s_barrier
	ds_read_b128 v[46:49], v40 offset:32768
	ds_read_b128 v[50:53], v40 offset:33792
	ds_read_b128 v[54:57], v40 offset:34816
	ds_read_b128 v[58:61], v40 offset:35840
	ds_read_b128 v[62:65], v40 offset:36864
	ds_read_b128 v[66:69], v40 offset:37888
	ds_read_b128 v[70:73], v40 offset:38912
	ds_read_b128 v[74:77], v40 offset:39936
	ds_read_b128 v[78:81], v43
	ds_read_b128 v[82:85], v43 offset:1024
	ds_read_b128 v[86:89], v43 offset:2048
	ds_read_b128 v[90:93], v43 offset:3072
	s_setprio 1
	v_mfma_f32_16x16x32_bf16 v[28:31], v[234:237], v[202:205], v[28:31]
	v_mfma_f32_16x16x32_bf16 v[24:27], v[166:169], v[202:205], v[24:27]
	v_mfma_f32_16x16x32_bf16 v[20:23], v[234:237], v[210:213], v[20:23]
	v_mfma_f32_16x16x32_bf16 v[16:19], v[166:169], v[210:213], v[16:19]
	global_load_lds_dwordx4 v[104:105], off
	v_mfma_f32_16x16x32_bf16 v[12:15], v[234:237], v[218:221], v[12:15]
	v_mfma_f32_16x16x32_bf16 v[8:11], v[166:169], v[218:221], v[8:11]
	v_mfma_f32_16x16x32_bf16 v[4:7], v[234:237], v[226:229], v[4:7]
	v_mfma_f32_16x16x32_bf16 v[0:3], v[166:169], v[226:229], v[0:3]
	v_lshl_add_u64 v[104:105], s[34:35], 0, v[132:133]
	s_mov_b32 m0, s20
	s_nop 0
	global_load_lds_dwordx4 v[104:105], off
	v_mfma_f32_16x16x32_bf16 v[28:31], v[238:241], v[206:209], v[28:31]
	v_mfma_f32_16x16x32_bf16 v[24:27], v[170:173], v[206:209], v[24:27]
	v_mfma_f32_16x16x32_bf16 v[20:23], v[238:241], v[214:217], v[20:23]
	v_mfma_f32_16x16x32_bf16 v[16:19], v[170:173], v[214:217], v[16:19]
	v_lshl_add_u64 v[104:105], s[36:37], 0, v[136:137]
	s_mov_b32 m0, s13
	s_nop 0
	global_load_lds_dwordx4 v[104:105], off
	v_mfma_f32_16x16x32_bf16 v[12:15], v[238:241], v[222:225], v[12:15]
	v_mfma_f32_16x16x32_bf16 v[8:11], v[170:173], v[222:225], v[8:11]
	v_mfma_f32_16x16x32_bf16 v[4:7], v[238:241], v[230:233], v[4:7]
	v_mfma_f32_16x16x32_bf16 v[0:3], v[170:173], v[230:233], v[0:3]
	v_lshl_add_u64 v[104:105], s[34:35], 0, v[134:135]
	s_mov_b32 m0, s21
	s_nop 0
	global_load_lds_dwordx4 v[104:105], off
	s_setprio 0
	s_cmp_lt_u32 s27, 61
	s_cselect_b32 s33, 3, 0xffffffc3
	s_add_i32 s34, s27, s33
	s_ashr_i32 s35, s34, 31
	s_lshl_b64 s[34:35], s[34:35], 7
	s_add_u32 s36, s2, s34
	s_addc_u32 s37, s3, s35
	s_add_u32 s34, s4, s34
	s_mov_b32 m0, s14
	s_addc_u32 s35, s5, s35
	v_lshl_add_u64 v[104:105], s[36:37], 0, v[130:131]
	s_waitcnt lgkmcnt(0)
	s_waitcnt vmcnt(8)
	s_barrier
	ds_read_b128 v[202:205], v40 offset:49152
	ds_read_b128 v[206:209], v40 offset:50176
	ds_read_b128 v[210:213], v40 offset:51200
	ds_read_b128 v[214:217], v40 offset:52224
	ds_read_b128 v[218:221], v40 offset:53248
	ds_read_b128 v[222:225], v40 offset:54272
	ds_read_b128 v[226:229], v40 offset:55296
	ds_read_b128 v[230:233], v40 offset:56320
	ds_read_b128 v[234:237], v44
	ds_read_b128 v[238:241], v44 offset:1024
	ds_read_b128 v[166:169], v44 offset:2048
	ds_read_b128 v[170:173], v44 offset:3072
	s_setprio 1
	v_mfma_f32_16x16x32_bf16 v[28:31], v[78:81], v[46:49], v[28:31]
	v_mfma_f32_16x16x32_bf16 v[24:27], v[86:89], v[46:49], v[24:27]
	v_mfma_f32_16x16x32_bf16 v[20:23], v[78:81], v[54:57], v[20:23]
	v_mfma_f32_16x16x32_bf16 v[16:19], v[86:89], v[54:57], v[16:19]
	global_load_lds_dwordx4 v[104:105], off
	v_mfma_f32_16x16x32_bf16 v[12:15], v[78:81], v[62:65], v[12:15]
	v_mfma_f32_16x16x32_bf16 v[8:11], v[86:89], v[62:65], v[8:11]
	v_mfma_f32_16x16x32_bf16 v[4:7], v[78:81], v[70:73], v[4:7]
	v_mfma_f32_16x16x32_bf16 v[0:3], v[86:89], v[70:73], v[0:3]
	v_lshl_add_u64 v[104:105], s[34:35], 0, v[132:133]
	s_mov_b32 m0, s22
	s_nop 0
	global_load_lds_dwordx4 v[104:105], off
	v_mfma_f32_16x16x32_bf16 v[28:31], v[82:85], v[50:53], v[28:31]
	v_mfma_f32_16x16x32_bf16 v[24:27], v[90:93], v[50:53], v[24:27]
	v_mfma_f32_16x16x32_bf16 v[20:23], v[82:85], v[58:61], v[20:23]
	v_mfma_f32_16x16x32_bf16 v[16:19], v[90:93], v[58:61], v[16:19]
	v_lshl_add_u64 v[104:105], s[36:37], 0, v[136:137]
	s_mov_b32 m0, s15
	s_nop 0
	global_load_lds_dwordx4 v[104:105], off
	v_mfma_f32_16x16x32_bf16 v[12:15], v[82:85], v[66:69], v[12:15]
	v_mfma_f32_16x16x32_bf16 v[8:11], v[90:93], v[66:69], v[8:11]
	v_mfma_f32_16x16x32_bf16 v[4:7], v[82:85], v[74:77], v[4:7]
	v_mfma_f32_16x16x32_bf16 v[0:3], v[90:93], v[74:77], v[0:3]
	v_lshl_add_u64 v[104:105], s[34:35], 0, v[134:135]
	s_mov_b32 m0, s23
	s_nop 0
	global_load_lds_dwordx4 v[104:105], off
	s_setprio 0
	s_add_i32 s24, s24, 4
	s_add_u32 s30, s30, 0x200
	s_addc_u32 s31, s31, 0
	s_cmp_lt_u32 s24, 60
	s_cbranch_scc1 .LBB0_2166
	s_waitcnt lgkmcnt(0)
	s_setprio 1
	v_mfma_f32_16x16x32_bf16 v[28:31], v[234:237], v[202:205], v[28:31]
	v_mfma_f32_16x16x32_bf16 v[24:27], v[166:169], v[202:205], v[24:27]
	v_mfma_f32_16x16x32_bf16 v[20:23], v[234:237], v[210:213], v[20:23]
	v_mfma_f32_16x16x32_bf16 v[16:19], v[166:169], v[210:213], v[16:19]
	v_mfma_f32_16x16x32_bf16 v[12:15], v[234:237], v[218:221], v[12:15]
	v_mfma_f32_16x16x32_bf16 v[8:11], v[166:169], v[218:221], v[8:11]
	v_mfma_f32_16x16x32_bf16 v[4:7], v[234:237], v[226:229], v[4:7]
	v_mfma_f32_16x16x32_bf16 v[0:3], v[166:169], v[226:229], v[0:3]
	v_mfma_f32_16x16x32_bf16 v[28:31], v[238:241], v[206:209], v[28:31]
	v_mfma_f32_16x16x32_bf16 v[24:27], v[170:173], v[206:209], v[24:27]
	v_mfma_f32_16x16x32_bf16 v[20:23], v[238:241], v[214:217], v[20:23]
	v_mfma_f32_16x16x32_bf16 v[16:19], v[170:173], v[214:217], v[16:19]
	v_mfma_f32_16x16x32_bf16 v[12:15], v[238:241], v[222:225], v[12:15]
	v_mfma_f32_16x16x32_bf16 v[8:11], v[170:173], v[222:225], v[8:11]
	v_mfma_f32_16x16x32_bf16 v[4:7], v[238:241], v[230:233], v[4:7]
	v_mfma_f32_16x16x32_bf16 v[0:3], v[170:173], v[230:233], v[0:3]
	s_setprio 0
	s_lshl_b32 s0, s0, 7
	s_lshl_b32 s2, s8, 7
	s_or_b32 s0, s1, s0
	s_add_i32 s9, s9, s2
	v_or_b32_e32 v34, s0, v152
	v_or_b32_e32 v32, s9, v163
	v_ashrrev_i32_e32 v35, 31, v34
	v_mov_b32_e32 v33, 0
	v_lshl_add_u64 v[36:37], v[34:35], 1, s[6:7]
	v_lshlrev_b64 v[38:39], 13, v[32:33]
	v_lshl_add_u64 v[38:39], v[36:37], 0, v[38:39]
	s_waitcnt vmcnt(0)
	s_barrier
	global_load_dwordx4 v[38:41], v[38:39], off
	v_lshl_add_u64 v[34:35], v[34:35], 2, s[28:29]
	v_lshlrev_b64 v[42:43], 14, v[32:33]
	v_lshl_add_u64 v[50:51], v[34:35], 0, v[42:43]
	global_load_dwordx4 v[42:45], v[50:51], off
	global_load_dwordx4 v[46:49], v[50:51], off offset:16
	v_mul_f32_e32 v28, 0xbfb8aa3b, v28
	v_mul_f32_e32 v29, 0xbfb8aa3b, v29
	v_mul_f32_e32 v30, 0xbfb8aa3b, v30
	v_mul_f32_e32 v31, 0xbfb8aa3b, v31
	v_mul_f32_e32 v24, 0xbfb8aa3b, v24
	v_mul_f32_e32 v25, 0xbfb8aa3b, v25
	v_mul_f32_e32 v26, 0xbfb8aa3b, v26
	v_mul_f32_e32 v27, 0xbfb8aa3b, v27
	v_exp_f32_e32 v28, v28
	v_exp_f32_e32 v29, v29
	v_exp_f32_e32 v30, v30
	v_exp_f32_e32 v31, v31
	v_exp_f32_e32 v54, v24
	v_exp_f32_e32 v55, v25
	v_exp_f32_e32 v26, v26
	v_exp_f32_e32 v27, v27
	v_mov_b32_e32 v53, v33
	v_or_b32_e32 v52, 16, v32
	v_lshlrev_b64 v[24:25], 13, v[52:53]
	v_add_f32_e32 v28, 1.0, v28
	v_add_f32_e32 v29, 1.0, v29
	v_add_f32_e32 v30, 1.0, v30
	v_add_f32_e32 v31, 1.0, v31
	v_add_f32_e32 v56, 1.0, v54
	v_add_f32_e32 v57, 1.0, v55
	v_add_f32_e32 v58, 1.0, v26
	v_add_f32_e32 v59, 1.0, v27
	v_lshl_add_u64 v[54:55], v[36:37], 0, v[24:25]
	v_rcp_f32_e32 v24, v28
	v_rcp_f32_e32 v25, v29
	v_rcp_f32_e32 v26, v30
	v_rcp_f32_e32 v27, v31
	v_rcp_f32_e32 v28, v56
	v_rcp_f32_e32 v29, v57
	v_rcp_f32_e32 v30, v58
	v_rcp_f32_e32 v31, v59
	v_mul_f32_e32 v20, 0xbfb8aa3b, v20
	v_mul_f32_e32 v21, 0xbfb8aa3b, v21
	v_mul_f32_e32 v22, 0xbfb8aa3b, v22
	v_mul_f32_e32 v23, 0xbfb8aa3b, v23
	v_mul_f32_e32 v16, 0xbfb8aa3b, v16
	v_mul_f32_e32 v17, 0xbfb8aa3b, v17
	v_mul_f32_e32 v18, 0xbfb8aa3b, v18
	v_mul_f32_e32 v19, 0xbfb8aa3b, v19
	v_exp_f32_e32 v20, v20
	v_exp_f32_e32 v21, v21
	v_exp_f32_e32 v22, v22
	v_exp_f32_e32 v23, v23
	v_exp_f32_e32 v18, v18
	v_exp_f32_e32 v19, v19
	v_add_f32_e32 v20, 1.0, v20
	v_add_f32_e32 v21, 1.0, v21
	v_add_f32_e32 v22, 1.0, v22
	v_add_f32_e32 v23, 1.0, v23
	v_mul_f32_e32 v12, 0xbfb8aa3b, v12
	v_mul_f32_e32 v13, 0xbfb8aa3b, v13
	v_mul_f32_e32 v14, 0xbfb8aa3b, v14
	v_mul_f32_e32 v15, 0xbfb8aa3b, v15
	v_mul_f32_e32 v8, 0xbfb8aa3b, v8
	v_mul_f32_e32 v9, 0xbfb8aa3b, v9
	v_mul_f32_e32 v10, 0xbfb8aa3b, v10
	v_mul_f32_e32 v11, 0xbfb8aa3b, v11
	v_exp_f32_e32 v12, v12
	v_exp_f32_e32 v13, v13
	v_exp_f32_e32 v14, v14
	v_exp_f32_e32 v15, v15
	v_exp_f32_e32 v10, v10
	v_exp_f32_e32 v11, v11
	v_add_f32_e32 v12, 1.0, v12
	v_add_f32_e32 v13, 1.0, v13
	v_add_f32_e32 v14, 1.0, v14
	v_add_f32_e32 v15, 1.0, v15
	v_mul_f32_e32 v4, 0xbfb8aa3b, v4
	v_mul_f32_e32 v5, 0xbfb8aa3b, v5
	v_mul_f32_e32 v6, 0xbfb8aa3b, v6
	s_waitcnt vmcnt(0)
	v_lshlrev_b32_e32 v56, 16, v38
	v_and_b32_e32 v57, 0xffff0000, v38
	v_lshlrev_b32_e32 v38, 16, v39
	v_and_b32_e32 v39, 0xffff0000, v39
	v_lshlrev_b32_e32 v58, 16, v40
	v_and_b32_e32 v59, 0xffff0000, v40
	v_lshlrev_b32_e32 v40, 16, v41
	v_and_b32_e32 v41, 0xffff0000, v41
	v_pk_fma_f32 v[26:27], v[26:27], v[38:39], v[44:45]
	v_pk_fma_f32 v[24:25], v[24:25], v[56:57], v[42:43]
	v_pk_fma_f32 v[30:31], v[30:31], v[40:41], v[48:49]
	v_pk_fma_f32 v[28:29], v[28:29], v[58:59], v[46:47]
	global_store_dwordx4 v[50:51], v[24:27], off
	global_store_dwordx4 v[50:51], v[28:31], off offset:16
	global_load_dwordx4 v[24:27], v[54:55], off
	v_exp_f32_e32 v46, v16
	v_lshlrev_b64 v[28:29], 14, v[52:53]
	v_lshl_add_u64 v[42:43], v[34:35], 0, v[28:29]
	global_load_dwordx4 v[28:31], v[42:43], off
	global_load_dwordx4 v[38:41], v[42:43], off offset:16
	v_exp_f32_e32 v47, v17
	v_mov_b32_e32 v45, v33
	v_or_b32_e32 v44, 32, v32
	v_lshlrev_b64 v[16:17], 13, v[44:45]
	v_add_f32_e32 v48, 1.0, v46
	v_add_f32_e32 v49, 1.0, v47
	v_add_f32_e32 v50, 1.0, v18
	v_add_f32_e32 v51, 1.0, v19
	v_lshl_add_u64 v[46:47], v[36:37], 0, v[16:17]
	v_rcp_f32_e32 v16, v20
	v_rcp_f32_e32 v17, v21
	v_rcp_f32_e32 v18, v22
	v_rcp_f32_e32 v19, v23
	v_rcp_f32_e32 v20, v48
	v_rcp_f32_e32 v21, v49
	v_rcp_f32_e32 v22, v50
	v_rcp_f32_e32 v23, v51
	v_or_b32_e32 v32, 48, v32
	v_mul_f32_e32 v7, 0xbfb8aa3b, v7
	v_mul_f32_e32 v0, 0xbfb8aa3b, v0
	v_mul_f32_e32 v1, 0xbfb8aa3b, v1
	v_mul_f32_e32 v2, 0xbfb8aa3b, v2
	v_mul_f32_e32 v3, 0xbfb8aa3b, v3
	v_exp_f32_e32 v4, v4
	v_exp_f32_e32 v5, v5
	v_exp_f32_e32 v6, v6
	v_exp_f32_e32 v7, v7
	v_exp_f32_e32 v0, v0
	v_exp_f32_e32 v1, v1
	v_exp_f32_e32 v2, v2
	v_exp_f32_e32 v3, v3
	v_add_f32_e32 v4, 1.0, v4
	v_add_f32_e32 v5, 1.0, v5
	v_add_f32_e32 v6, 1.0, v6
	v_add_f32_e32 v7, 1.0, v7
	s_waitcnt vmcnt(2)
	v_lshlrev_b32_e32 v48, 16, v24
	v_and_b32_e32 v49, 0xffff0000, v24
	v_lshlrev_b32_e32 v24, 16, v25
	v_and_b32_e32 v25, 0xffff0000, v25
	v_lshlrev_b32_e32 v50, 16, v26
	v_and_b32_e32 v51, 0xffff0000, v26
	v_lshlrev_b32_e32 v26, 16, v27
	v_and_b32_e32 v27, 0xffff0000, v27
	s_waitcnt vmcnt(1)
	v_pk_fma_f32 v[18:19], v[18:19], v[24:25], v[30:31]
	v_pk_fma_f32 v[16:17], v[16:17], v[48:49], v[28:29]
	s_waitcnt vmcnt(0)
	v_pk_fma_f32 v[22:23], v[22:23], v[26:27], v[40:41]
	v_pk_fma_f32 v[20:21], v[20:21], v[50:51], v[38:39]
	global_store_dwordx4 v[42:43], v[16:19], off
	global_store_dwordx4 v[42:43], v[20:23], off offset:16
	global_load_dwordx4 v[16:19], v[46:47], off
	v_exp_f32_e32 v30, v8
	v_lshlrev_b64 v[20:21], 14, v[44:45]
	v_lshl_add_u64 v[28:29], v[34:35], 0, v[20:21]
	global_load_dwordx4 v[20:23], v[28:29], off
	global_load_dwordx4 v[24:27], v[28:29], off offset:16
	v_exp_f32_e32 v31, v9
	v_lshlrev_b64 v[8:9], 13, v[32:33]
	v_add_f32_e32 v38, 1.0, v30
	v_add_f32_e32 v40, 1.0, v10
	v_add_f32_e32 v39, 1.0, v31
	v_add_f32_e32 v41, 1.0, v11
	v_lshl_add_u64 v[30:31], v[36:37], 0, v[8:9]
	v_rcp_f32_e32 v8, v12
	v_rcp_f32_e32 v9, v13
	v_rcp_f32_e32 v10, v14
	v_rcp_f32_e32 v11, v15
	v_rcp_f32_e32 v12, v38
	v_rcp_f32_e32 v13, v39
	v_rcp_f32_e32 v14, v40
	v_rcp_f32_e32 v15, v41
	s_waitcnt vmcnt(2)
	v_lshlrev_b32_e32 v36, 16, v16
	v_and_b32_e32 v37, 0xffff0000, v16
	v_lshlrev_b32_e32 v16, 16, v17
	v_and_b32_e32 v17, 0xffff0000, v17
	v_lshlrev_b32_e32 v38, 16, v18
	v_and_b32_e32 v39, 0xffff0000, v18
	v_lshlrev_b32_e32 v18, 16, v19
	v_and_b32_e32 v19, 0xffff0000, v19
	s_waitcnt vmcnt(1)
	v_pk_fma_f32 v[10:11], v[10:11], v[16:17], v[22:23]
	v_pk_fma_f32 v[8:9], v[8:9], v[36:37], v[20:21]
	s_waitcnt vmcnt(0)
	v_pk_fma_f32 v[14:15], v[14:15], v[18:19], v[26:27]
	v_pk_fma_f32 v[12:13], v[12:13], v[38:39], v[24:25]
	global_store_dwordx4 v[28:29], v[8:11], off
	global_store_dwordx4 v[28:29], v[12:15], off offset:16
	global_load_dwordx4 v[8:11], v[30:31], off
	v_add_f32_e32 v22, 1.0, v0
	v_lshlrev_b64 v[12:13], 14, v[32:33]
	v_lshl_add_u64 v[20:21], v[34:35], 0, v[12:13]
	global_load_dwordx4 v[12:15], v[20:21], off
	global_load_dwordx4 v[16:19], v[20:21], off offset:16
	v_add_f32_e32 v23, 1.0, v1
	v_add_f32_e32 v24, 1.0, v2
	v_add_f32_e32 v25, 1.0, v3
	v_rcp_f32_e32 v0, v4
	v_rcp_f32_e32 v1, v5
	v_rcp_f32_e32 v2, v6
	v_rcp_f32_e32 v3, v7
	v_rcp_f32_e32 v4, v22
	v_rcp_f32_e32 v5, v23
	v_rcp_f32_e32 v6, v24
	v_rcp_f32_e32 v7, v25
	s_waitcnt vmcnt(2)
	v_lshlrev_b32_e32 v22, 16, v8
	v_and_b32_e32 v23, 0xffff0000, v8
	v_lshlrev_b32_e32 v8, 16, v9
	v_and_b32_e32 v9, 0xffff0000, v9
	v_lshlrev_b32_e32 v24, 16, v10
	v_and_b32_e32 v25, 0xffff0000, v10
	v_lshlrev_b32_e32 v10, 16, v11
	v_and_b32_e32 v11, 0xffff0000, v11
	s_waitcnt vmcnt(1)
	v_pk_fma_f32 v[2:3], v[2:3], v[8:9], v[14:15]
	v_pk_fma_f32 v[0:1], v[0:1], v[22:23], v[12:13]
	s_waitcnt vmcnt(0)
	v_pk_fma_f32 v[6:7], v[6:7], v[10:11], v[18:19]
	v_pk_fma_f32 v[4:5], v[4:5], v[24:25], v[16:17]
	global_store_dwordx4 v[20:21], v[0:3], off
	global_store_dwordx4 v[20:21], v[4:7], off offset:16
